# static s_setprio 3 for the RWKV-scan consumer waves (0-3) during MIX_O, reset at phase end; on top of best stack
# speedup vs baseline: 1.0005x; 1.0005x over previous
; __device__ __forceinline__ int TID() { int t = threadIdx.x; asm volatile("" : "+v"(t)); return t; }
; __device__ __forceinline__ int BID() { int b = blockIdx.x; asm volatile("" : "+s"(b)); return b; }
; __device__ __forceinline__ int GSZ() { int g = gridDim.x; asm volatile("" : "+s"(g)); return g; }
; __device__ __forceinline__ int rfl(int v) { return __builtin_amdgcn_readfirstlane(v); }
;     ...
;     const int tid = TID(), wave = rfl(tid >> 6), lane = tid & 63, bid = BID(), gsz = GSZ();
;     const bool consumer = wave < 4;
.Lmo_noperm:
	s_cmp_lt_i32 s2, 4
	s_cbranch_scc0 .Lmo_noprio
	s_setprio 3

;     ...
;     if (!consumer && prevd.ok) P_REDUCE(prevd, (q + 1) & 1);
;     __syncthreads();
.LBB0_976:
	s_movk_i32 s55, 0x1000
	s_mov_b32 s61, 0x14f00000
	s_setprio 0
	s_barrier
